# v3 + the 32 sample-scan workgroups run 10 sample-group neighbourhood-attention items each after their scan (prompt NA workgroups stop at item 1216)
# baseline (speedup 1.0000x reference)
; #define LAS __attribute__((address_space(3)))
; #define GB_MIX(g)  ((h16*)gbuf(ws, g, OFF_MIX, 2048))
; #define GB_RR(g)   ((h16*)gbuf(ws, g, OFF_RR, 1024))
; #define GB_RK(g)   ((h16*)gbuf(ws, g, OFF_RK, 1024))
; #define GB_RV(g)   ((h16*)gbuf(ws, g, OFF_RV, 1024))
; #define GB_LOWS(g) ((h16*)gbuf(ws, g, OFF_LOWS, 768))
; #define GB_YB(g)   ((h16*)gbuf(ws, g, OFF_YB, 1024))
; #define GB_BSC(g)  ((float*)gbuf(ws, g, OFF_BSC, 64))
; template <int R>
; __device__ __forceinline__ void scan_item(const Args& a, int layer, int q, int rowhalf, LAS unsigned char* lds, int tid, int lane, int wave) {
;     int tok0, T, h, d;
;     if (q < 32) { tok0 = MP + (q >> 4) * TS; T = TS; h = (q >> 1) & 7; d = q & 1; } else { const int q2 = q - 32; tok0 = (q2 >> 4) * TP; T = TP; h = (q2 >> 1) & 7; d = q2 & 1; }
;     const int nch = T / SC_CH, rowbase = rowhalf * 16 * R;
;     unsigned char* ws = a.ws; const int g = q < 32 ? 1 : 0;
;     const h16* RR = GB_RR(g); const h16* RK = GB_RK(g); const h16* RV = GB_RV(g); const h16* LOWS = GB_LOWS(g);
;     h16* Yf = GB_MIX(g); h16* Yb = GB_YB(g); float* BSC = GB_BSC(g);
;     const size_t l = (size_t)layer;
;     if (wave >= 4) {
;     ...
;         constexpr int RL = R / 2;
;         const int ri = lane >> 3, ci = lane & 7;
;         const int yrow = wave * 8 * RL + ri * RL, vrow = rowbase + yrow;
;         f32x2 S[RL][4];
; #pragma unroll
;         for (int i = 0; i < RL; ++i)
; #pragma unroll
;             for (int c2 = 0; c2 < 4; ++c2) S[i][c2] = (f32x2){0.f, 0.f};
;         typedef float vecR __attribute__((ext_vector_type(RL)));
;         __syncthreads();
.LBB0_409:
	s_or_b64 exec, exec, s[2:3]
	v_mov_b32_e32 v190, v199
	s_barrier
	s_waitcnt vmcnt(0)
	buffer_inv sc1
	s_waitcnt vmcnt(0)
	s_mov_b32 s4, 0
	v_writelane_b32 v255, s4, 57
	s_mov_b64 s[2:3], -1
	v_readfirstlane_b32 s26, v190
	s_ashr_i32 s4, s26, 6
	s_cmp_lt_i32 s4, 4
	v_writelane_b32 v254, s4, 48
	s_cselect_b64 s[4:5], -1, 0
	v_writelane_b32 v254, s4, 49
	s_and_b64 vcc, exec, s[4:5]
	s_nop 0
	v_writelane_b32 v254, s5, 50
	s_cbranch_vccz .LBB0_423
	v_lshrrev_b32_e32 v1, 2, v190
	v_and_b32_e32 v1, 14, v1
	v_readlane_b32 s2, v254, 48
	v_and_b32_e32 v0, 7, v190
	v_mov_b32_e32 v152, v153
	v_lshl_or_b32 v100, s2, 4, v1
	s_lshl_b32 s2, s2, 6
	v_and_b32_e32 v1, 56, v190
	v_or_b32_e32 v102, s2, v1
	s_addk_i32 s2, 0xb00
	v_or_b32_e32 v103, s2, v1
	v_mov_b32_e32 v1, 0x600
	v_lshlrev_b32_e32 v101, 1, v0
	s_mov_b32 s6, 0
	v_cmp_eq_u32_e32 vcc, 0, v0
	v_lshl_or_b32 v104, v0, 5, v1
	s_mov_b64 s[4:5], 0
	v_mov_b64_e32 v[82:83], v[152:153]
	v_mov_b64_e32 v[84:85], v[152:153]
	v_mov_b64_e32 v[86:87], v[152:153]
	v_mov_b64_e32 v[88:89], v[152:153]
	v_mov_b64_e32 v[90:91], v[152:153]
	v_mov_b64_e32 v[92:93], v[152:153]
	v_mov_b64_e32 v[94:95], v[152:153]
	v_mov_b64_e32 v[96:97], v[152:153]
	s_barrier
	s_branch .LBB0_412

; __global__ void __launch_bounds__(NTHREADS, 2) fwd_megakernel(Args args) {
;     ...
;               if (pb < 2 * (256 - NPB)) { scan_item<2>(args, layer, 32 + NPB + (pb >> 1), pb & 1, lds, tid, lane, wave); __syncthreads(); }
;               else { for (int it = pb - 2 * (256 - NPB); it < 1536; it += NPB - 2 * (256 - NPB)) na_item(args, layer, it, lds, tid, lane, wave); } }
.LBB0_446:
	v_readlane_b32 s4, v249, 50
	v_readlane_b32 s5, v249, 51
	s_mov_b64 s[2:3], -1
	s_and_b64 vcc, exec, s[4:5]
	s_barrier
	s_cbranch_vccz .LBB0_466
	v_readlane_b32 s2, v249, 53
	v_writelane_b32 v254, s92, 52
	v_readlane_b32 s3, v249, 54
	s_andn2_b64 vcc, exec, s[2:3]
	v_writelane_b32 v254, s93, 53
	s_cbranch_vccnz .LBB0_465
	v_readlane_b32 s2, v249, 52
	s_nop 1
	v_writelane_b32 v255, s2, 62
	v_readlane_b32 s2, v249, 55
	s_nop 1
	v_writelane_b32 v255, s2, 63
	s_movk_i32 s2, 0x4c0
	v_writelane_b32 v255, s2, 61
; __device__ __forceinline__ void na_item(const Args& a, int layer, int item, LAS unsigned char* lds, int tid, int lane, int wave) {
;     ...
;     const int j = lane, aw = wave;
;     const int tokq = tok0 + i * 64 + j;
;     int cs = j - 8; cs = cs < 0 ? 0 : (cs > 48 ? 48 : cs);
;     const int l31 = lane & 31, half = lane >> 5;
;     LAS float* bt = (LAS float*)(lds + NA_BTOFF) + wave * 128;
;     bt[lane] = 0.f; bt[64 + lane] = 0.f;
;     u32x4 kreg[8], vreg[8];
;     const size_t kvoff = (size_t)(wtok0 + (tid >> 3)) * 512 + (tid & 7) * 8;
; #pragma unroll
;     for (int it = 0; it < 8; ++it) { kreg[it] = *(const u32x4*)(KNA + kvoff + (size_t)it * (64 * 512)); vreg[it] = *(const u32x4*)(VNA + kvoff + (size_t)it * (64 * 512)); }
; #pragma unroll 1
;     for (int h = 0; h < 8; ++h) {
; #pragma unroll
;         for (int it = 0; it < 8; ++it) { const int key = (tid >> 3) + 64 * it, ch = tid & 7;
;             *(LAS u32x4*)(lds + key * NA_PITCH + ch * 16) = kreg[it]; *(LAS u32x4*)(lds + NA_VOFF + key * NA_PITCH + ch * 16) = vreg[it]; }
;         h16x8 qf[2][4];
; #pragma unroll
;         for (int nt = 0; nt < 2; ++nt)
; #pragma unroll
;             for (int ks = 0; ks < 4; ++ks) qf[nt][ks] = *(const h16x8*)(MIX + (size_t)(tok0 + i * 64 + l31 + 32 * nt) * 1024 + h * 64 + 16 * ks + 8 * half);
;         if (lane < 31) bt[48 + lane] = rpb[((size_t)h * 15 + (rs + aw - i + 7)) * 31 + lane];
;         __syncthreads();
;         if (h + 1 < 8) {
; #pragma unroll
;             for (int it = 0; it < 8; ++it) { kreg[it] = *(const u32x4*)(KNA + kvoff + (size_t)it * (64 * 512) + (h + 1) * 64); vreg[it] = *(const u32x4*)(VNA + kvoff + (size_t)it * (64 * 512) + (h + 1) * 64); }
;         }
;         f32x16 acc[2][2];
; #pragma unroll
;         for (int mt = 0; mt < 2; ++mt)
; #pragma unroll
;             for (int nt = 0; nt < 2; ++nt)
; #pragma unroll
;                 for (int r = 0; r < 16; ++r) acc[mt][nt][r] = 0.f;
; #pragma unroll
;         for (int mt = 0; mt < 2; ++mt)
; #pragma unroll
;             for (int ks = 0; ks < 4; ++ks) {
;                 const h16x8 kf = *(const LAS h16x8*)(lds + (aw * 64 + 32 * mt + l31) * NA_PITCH + (16 * ks + 8 * half) * 2);
;                 acc[mt][0] = __builtin_amdgcn_mfma_f32_32x32x16_f16(kf, qf[0][ks], acc[mt][0], 0, 0, 0);
;                 acc[mt][1] = __builtin_amdgcn_mfma_f32_32x32x16_f16(kf, qf[1][ks], acc[mt][1], 0, 0, 0);
.Lna_setup:
	v_readlane_b32 s4, v254, 48
	v_lshrrev_b32_e32 v1, 5, v171
	v_and_b32_e32 v191, 31, v190
	s_lshl_b32 s2, s4, 9
	v_lshlrev_b32_e32 v6, 2, v1
	s_add_i32 s2, s2, 0
	v_or_b32_e32 v7, 8, v6
	v_max_u32_e32 v12, 8, v191
	s_add_i32 s2, s2, 0x24000
	s_add_i32 s4, s4, 7
	v_sub_u32_e32 v13, v6, v191
	v_sub_u32_e32 v12, v7, v12
	v_writelane_b32 v254, s4, 54
	v_lshl_add_u32 v196, v13, 2, s2
	v_cmp_gt_u32_e64 s[6:7], 16, v12
	v_add_u32_e32 v13, 1, v12
	v_cmp_gt_u32_e64 s[20:21], 16, v13
	v_writelane_b32 v254, s6, 55
	v_add_u32_e32 v13, 2, v12
	s_andn2_b32 s26, s26, 63
	v_writelane_b32 v254, s7, 56
	v_cmp_gt_u32_e64 s[6:7], 16, v13
	v_add_u32_e32 v13, 3, v12
	v_or_b32_e32 v4, s26, v191
	v_or_b32_e32 v8, s26, v6
	v_cmp_gt_u32_e64 s[26:27], 16, v13
	v_add_u32_e32 v13, 8, v12
	v_cmp_gt_u32_e64 s[28:29], 16, v13
	v_add_u32_e32 v13, 9, v12
	v_cmp_gt_u32_e64 s[22:23], 16, v13
	v_add_u32_e32 v13, 10, v12
	v_cmp_gt_u32_e64 s[34:35], 16, v13
	v_add_u32_e32 v13, 11, v12
	v_cmp_gt_u32_e64 s[54:55], 16, v13
	v_add_u32_e32 v13, 17, v12
	v_cmp_gt_u32_e64 s[62:63], 16, v13
	v_add_u32_e32 v13, 18, v12
	v_cmp_gt_u32_e64 s[52:53], 16, v13
	v_add_u32_e32 v13, 19, v12
	v_cmp_gt_u32_e64 s[56:57], 16, v13
	v_add_u32_e32 v13, 24, v12
	v_cmp_gt_u32_e64 s[60:61], 16, v13
	v_add_u32_e32 v13, 25, v12
	v_cmp_gt_u32_e64 s[64:65], 16, v13
	v_add_u32_e32 v13, 26, v12
	s_movk_i32 s4, 0xffef
	v_cmp_gt_u32_e64 s[66:67], 16, v13
	v_add_u32_e32 v13, 27, v12
	v_cmp_lt_u32_e64 s[58:59], s4, v12
	v_cmp_gt_u32_e64 s[68:69], 16, v13
	v_and_b32_e32 v13, -16, v12
	s_movk_i32 s4, 0xffe0
	v_cmp_eq_u32_e64 s[70:71], s4, v13
	v_add_u32_e32 v13, 33, v12
	v_cmp_gt_u32_e64 s[72:73], 16, v13
	v_add_u32_e32 v13, 34, v12
	v_add_u32_e32 v12, 35, v12
	v_cmp_gt_u32_e64 s[76:77], 16, v12
	v_or_b32_e32 v12, 32, v171
	v_cmp_gt_u32_e64 s[74:75], 16, v13
	v_min_u32_e32 v13, 56, v12
	v_sub_u32_e32 v6, v6, v12
	v_lshl_add_u32 v197, v6, 2, s2
	v_sub_u32_e32 v6, v7, v13
	v_add_u32_e32 v7, 17, v6
	v_cmp_gt_u32_e64 s[78:79], 16, v7
	v_add_u32_e32 v7, 18, v6
	v_cmp_gt_u32_e64 s[80:81], 16, v7
	v_add_u32_e32 v7, 19, v6
	v_cmp_gt_u32_e64 s[82:83], 16, v7
	v_add_u32_e32 v7, 24, v6
	v_cmp_gt_u32_e64 s[84:85], 16, v7
	v_add_u32_e32 v7, 25, v6
	v_cmp_gt_u32_e64 s[86:87], 16, v7
	v_add_u32_e32 v7, 26, v6
	v_lshlrev_b32_e32 v152, 2, v171
	v_cmp_gt_u32_e64 s[88:89], 16, v7
	v_add_u32_e32 v7, 27, v6
	v_add_u32_e32 v192, s2, v152
	v_writelane_b32 v254, s6, 57
	v_cmp_gt_u32_e64 s[90:91], 16, v7
	v_and_b32_e32 v7, -16, v6
	s_movk_i32 s2, 0xffd0
	v_writelane_b32 v254, s7, 58
	v_cmp_eq_u32_e64 s[24:25], s2, v7
	v_cmp_eq_u32_e64 s[92:93], s4, v7
	v_add_u32_e32 v7, 49, v6
	v_writelane_b32 v254, s24, 59
	v_add_u32_e32 v12, 33, v6
	v_cmp_gt_u32_e64 s[94:95], 16, v12
	v_writelane_b32 v254, s25, 60
	v_cmp_gt_u32_e64 s[24:25], 16, v7
	v_add_u32_e32 v7, 50, v6
	v_add_u32_e32 v12, 34, v6
	v_writelane_b32 v254, s24, 61
	v_cmp_gt_u32_e64 s[96:97], 16, v12
	v_add_u32_e32 v12, 35, v6
	v_writelane_b32 v254, s25, 62
	v_cmp_gt_u32_e64 s[24:25], 16, v7
	v_add_u32_e32 v7, 51, v6
	v_cmp_gt_u32_e64 s[6:7], 16, v12
	v_writelane_b32 v254, s24, 63
	v_add_u32_e32 v12, 40, v6
	v_cmp_gt_u32_e64 s[12:13], 16, v12
	v_writelane_b32 v255, s25, 0
	v_cmp_gt_u32_e64 s[24:25], 16, v7
	v_add_u32_e32 v7, 56, v6
	v_add_u32_e32 v12, 41, v6
	v_writelane_b32 v255, s24, 1
	v_cmp_gt_u32_e64 s[10:11], 16, v12
	v_add_u32_e32 v12, 42, v6
	v_writelane_b32 v255, s25, 2
	v_cmp_gt_u32_e64 s[24:25], 16, v7
	v_add_u32_e32 v7, 57, v6
	v_and_b32_e32 v0, 7, v190
	v_writelane_b32 v255, s24, 3
	s_movk_i32 s5, 0x90
	v_cmp_gt_u32_e64 s[14:15], 16, v12
	v_writelane_b32 v255, s25, 4
	v_cmp_gt_u32_e64 s[24:25], 16, v7
	v_add_u32_e32 v7, 58, v6
	v_add_u32_e32 v12, 43, v6
	v_writelane_b32 v255, s24, 5
	v_add_u32_e32 v6, 59, v6
	v_lshlrev_b32_e32 v170, 3, v0
	v_writelane_b32 v255, s25, 6
	v_cmp_gt_u32_e64 s[24:25], 16, v7
	v_lshlrev_b32_e32 v0, 4, v0
	s_add_i32 s3, 0, 0x12000
	v_writelane_b32 v255, s24, 7
	v_lshlrev_b32_e32 v9, 1, v191
	s_movk_i32 s2, 0x10c
	v_writelane_b32 v255, s25, 8
	v_cmp_gt_u32_e64 s[24:25], 16, v6
	v_mul_lo_u32 v6, v8, s5
	v_add_u32_e32 v3, s3, v0
	v_mul_lo_u32 v11, v4, s5
	v_add3_u32 v198, s3, v9, v6
	v_mul_lo_u32 v4, v4, s2
	v_mad_u32_u24 v213, v171, s2, 0
	v_readlane_b32 s2, v254, 36
	v_readlane_b32 s3, v254, 37
	v_readlane_b32 s36, v248, 16
	s_mul_hi_u32 s3, s2, 0x3a20
	s_mulk_i32 s2, 0x3a20
	v_readlane_b32 s40, v248, 20
	v_readlane_b32 s41, v248, 21
	s_add_u32 s2, s40, s2
	v_add_u32_e32 v2, 0, v0
	v_ashrrev_i32_e32 v0, 6, v190
	s_addc_u32 s3, s41, s3
	s_waitcnt vmcnt(9)
	v_lshlrev_b32_e32 v195, 5, v0
	v_lshlrev_b32_e32 v0, 3, v0
	v_lshl_add_u64 v[172:173], s[2:3], 0, v[152:153]
	v_readlane_b32 s2, v254, 29
	v_lshlrev_b32_e32 v194, 4, v1
	v_ashrrev_i32_e32 v1, 31, v0
	v_readlane_b32 s3, v254, 30
	v_ashrrev_i32_e32 v193, 3, v190
	v_readlane_b32 s42, v248, 22
	v_readlane_b32 s43, v248, 23
	v_readlane_b32 s46, v248, 26
	v_readlane_b32 s47, v248, 27
	v_readlane_b32 s48, v248, 28
	v_readlane_b32 s49, v248, 29
	v_lshl_add_u64 v[174:175], v[0:1], 1, s[2:3]
	v_lshrrev_b32_e32 v0, 1, v171
	v_cmp_gt_u32_e64 s[16:17], 31, v171
	v_add_u32_e32 v5, 0, v194
	v_mul_lo_u32 v10, v193, s5
	v_writelane_b32 v255, s24, 9
	s_waitcnt vmcnt(8)
	v_add_u32_e32 v211, 0, v4
	v_add_u32_e32 v4, 0x10c00, v213
	v_add_u32_e32 v6, 0x14f00, v213
	v_add_u32_e32 v7, 0x19200, v213
	v_add_u32_e32 v8, 0x1d500, v213
	v_readlane_b32 s38, v248, 18
	v_readlane_b32 s39, v248, 19
	v_readlane_b32 s44, v248, 24
	v_readlane_b32 s45, v248, 25
	v_readlane_b32 s46, v254, 16
	v_readlane_b32 s42, v254, 18
	v_readlane_b32 s48, v254, 12
	v_readlane_b32 s40, v254, 14
	v_and_b32_e32 v152, 16, v0
	v_cmp_gt_u32_e64 s[18:19], 32, v171
	v_cmp_gt_u32_e64 s[8:9], 16, v12
	v_writelane_b32 v255, s25, 10
	v_add_u32_e32 v212, 0x2180, v211
	s_waitcnt vmcnt(7)
	v_add_u32_e32 v214, 0x10d00, v213
	s_waitcnt vmcnt(6)
	v_add_u32_e32 v215, 0x15000, v213
	v_add_u32_e32 v216, 0x19300, v213
	v_add_u32_e32 v217, 0x1d600, v213
	v_readlane_b32 s47, v254, 17
	s_mov_b64 s[44:45], s[26:27]
	s_mov_b64 s[38:39], s[16:17]
	v_readlane_b32 s43, v254, 19
	v_readlane_b32 s49, v254, 13
	v_readlane_b32 s41, v254, 15
	v_lshl_add_u64 v[176:177], s[2:3], 0, v[152:153]
	v_add_u32_e32 v152, v2, v10
	v_add_u32_e32 v218, v3, v10
	v_add_u32_e32 v219, v5, v11
	s_waitcnt vmcnt(5)
	v_add_u32_e32 v220, v4, v195
	v_add_u32_e32 v221, v6, v195
	v_add_u32_e32 v222, v7, v195
	s_waitcnt vmcnt(4)
	v_add_u32_e32 v223, v8, v195
	v_readlane_b32 s24, v255, 62
	v_readlane_b32 s37, v248, 17
	v_readlane_b32 s50, v248, 30
	v_readlane_b32 s51, v248, 31
	s_branch .LBB0_450
.LBB0_449:
	v_readlane_b32 s2, v255, 63
	s_add_i32 s24, s2, s27
	v_readlane_b32 s3, v255, 61
	s_cmp_lt_i32 s24, s3
	s_cbranch_scc0 .LBB0_465

; #define SUBSYNC() do { sbt += (unsigned)NPB; sub_sync(ctr, sbt); } while (0)
; __global__ void __launch_bounds__(NTHREADS, 2) fwd_megakernel(Args args) {
;     ...
;               else { for (int it = pb - 2 * (256 - NPB); it < 1536; it += NPB - 2 * (256 - NPB)) na_item(args, layer, it, lds, tid, lane, wave); } }
;             SUBSYNC();
;             st_rwpost(args, layer, 0, NPB, pb, lds); SUBSYNC();
.LBB0_466:
	v_readlane_b32 s4, v255, 57
	s_cmp_eq_u32 s4, 3
	s_cbranch_scc0 .Lnas_cont
	s_mov_b32 s96, s86
	v_readlane_b32 s46, v254, 16
	v_readlane_b32 s47, v254, 17
	s_movk_i32 s72, 0xb00
	s_mov_b32 s77, 0x40000
	s_mov_b32 s73, 0x50000
	s_branch .Lnas_after

; __global__ void __launch_bounds__(NTHREADS, 2) fwd_megakernel(Args args) {
;     ...
;         if (bid < NSB) {
;             FRESH_TID scan_item<4>(args, layer, bid, 0, lds, tid, lane, wave);
;     ...
;               else { for (int it = pb - 2 * (256 - NPB); it < 1536; it += NPB - 2 * (256 - NPB)) na_item(args, layer, it, lds, tid, lane, wave); } }
.LBB0_662:
	s_waitcnt vmcnt(0) lgkmcnt(0)
	s_barrier
	v_mov_b32_e32 v190, v199
	v_and_b32_e32 v171, 63, v199
	s_add_i32 s4, s68, 0x4c0
	v_writelane_b32 v255, s4, 62
	s_movk_i32 s4, 32
	v_writelane_b32 v255, s4, 63
	s_movk_i32 s4, 0x600
	v_writelane_b32 v255, s4, 61
	s_mov_b32 s4, 3
	v_writelane_b32 v255, s4, 57
	v_readfirstlane_b32 s26, v190
	s_mov_b32 s93, 0
	s_lshr_b32 s4, s26, 6
	v_writelane_b32 v254, s4, 48
	v_writelane_b32 v254, s92, 52
	v_writelane_b32 v254, s93, 53
	s_branch .Lna_setup
